# phase 0 adaLN GEMV: weight rows loaded three iterations ahead (loop unrolled x4, rotating register sets)
# speedup vs baseline: 1.0132x; 1.0039x over previous
.LBB0_446:
	s_mul_hi_i32 s0, s8, 0x2aaaaaab
	s_lshr_b32 s1, s0, 31
	s_ashr_i32 s9, s0, 4
	s_add_i32 s9, s9, s1
	s_mul_i32 s0, s9, 0x60
	s_sub_i32 s0, s8, s0
	s_lshl_b32 s0, s0, 6
	s_ashr_i32 s1, s0, 31
	s_mul_i32 s11, s9, 0x1800000
	s_lshl_b64 s[4:5], s[0:1], 2
	s_mul_hi_i32 s10, s9, 0x1800000
	s_add_u32 s4, s11, s4
	s_addc_u32 s5, s10, s5
	v_mov_b32_e32 v6, 0
	v_lshl_add_u64 v[4:5], v[2:3], 0, s[4:5]
	s_mov_b64 s[4:5], 0
	s_mov_b32 s10, s7
	v_mov_b32_e32 v7, v6
	v_mov_b32_e32 v8, v6
	v_mov_b32_e32 v9, v6
	v_mov_b32_e32 v10, v6
	v_mov_b32_e32 v11, v6
	v_mov_b32_e32 v12, v6
	v_mov_b32_e32 v13, v6
	v_lshl_add_u64 v[178:179], v[4:5], 0, s[4:5]
	s_mov_b64 s[98:99], 0x6000
	global_load_dword v100, v[178:179], off
	v_lshl_add_u64 v[178:179], v[178:179], 0, s[98:99]
	global_load_dword v102, v[178:179], off
	v_lshl_add_u64 v[178:179], v[178:179], 0, s[98:99]
	global_load_dword v104, v[178:179], off
	v_lshl_add_u64 v[178:179], v[178:179], 0, s[98:99]
	global_load_dword v106, v[178:179], off
	v_lshl_add_u64 v[178:179], v[178:179], 0, s[98:99]
	global_load_dword v108, v[178:179], off
	v_lshl_add_u64 v[178:179], v[178:179], 0, s[98:99]
	global_load_dword v110, v[178:179], off
	v_lshl_add_u64 v[178:179], v[178:179], 0, s[98:99]
	global_load_dword v112, v[178:179], off
	v_lshl_add_u64 v[178:179], v[178:179], 0, s[98:99]
	global_load_dword v114, v[178:179], off
	v_lshl_add_u64 v[178:179], v[4:5], 0, s[4:5]
	s_mov_b64 s[98:99], 0x30000
	v_lshl_add_u64 v[178:179], v[178:179], 0, s[98:99]
	s_mov_b64 s[98:99], 0x6000
	global_load_dword v116, v[178:179], off
	v_lshl_add_u64 v[178:179], v[178:179], 0, s[98:99]
	global_load_dword v118, v[178:179], off
	v_lshl_add_u64 v[178:179], v[178:179], 0, s[98:99]
	global_load_dword v120, v[178:179], off
	v_lshl_add_u64 v[178:179], v[178:179], 0, s[98:99]
	global_load_dword v122, v[178:179], off
	v_lshl_add_u64 v[178:179], v[178:179], 0, s[98:99]
	global_load_dword v124, v[178:179], off
	v_lshl_add_u64 v[178:179], v[178:179], 0, s[98:99]
	global_load_dword v126, v[178:179], off
	v_lshl_add_u64 v[178:179], v[178:179], 0, s[98:99]
	global_load_dword v128, v[178:179], off
	v_lshl_add_u64 v[178:179], v[178:179], 0, s[98:99]
	global_load_dword v130, v[178:179], off
	v_lshl_add_u64 v[178:179], v[4:5], 0, s[4:5]
	s_mov_b64 s[98:99], 0x60000
	v_lshl_add_u64 v[178:179], v[178:179], 0, s[98:99]
	s_mov_b64 s[98:99], 0x6000
	global_load_dword v132, v[178:179], off
	v_lshl_add_u64 v[178:179], v[178:179], 0, s[98:99]
	global_load_dword v134, v[178:179], off
	v_lshl_add_u64 v[178:179], v[178:179], 0, s[98:99]
	global_load_dword v136, v[178:179], off
	v_lshl_add_u64 v[178:179], v[178:179], 0, s[98:99]
	global_load_dword v138, v[178:179], off
	v_lshl_add_u64 v[178:179], v[178:179], 0, s[98:99]
	global_load_dword v140, v[178:179], off
	v_lshl_add_u64 v[178:179], v[178:179], 0, s[98:99]
	global_load_dword v142, v[178:179], off
	v_lshl_add_u64 v[178:179], v[178:179], 0, s[98:99]
	global_load_dword v144, v[178:179], off
	v_lshl_add_u64 v[178:179], v[178:179], 0, s[98:99]
	global_load_dword v146, v[178:179], off
.LBB0_447:
	s_cmp_lt_u32 s4, 0x270000
	s_cbranch_scc0 .Lmod_nopf0
	v_lshl_add_u64 v[178:179], v[4:5], 0, s[4:5]
	s_mov_b64 s[98:99], 0x90000
	v_lshl_add_u64 v[178:179], v[178:179], 0, s[98:99]
	s_mov_b64 s[98:99], 0x6000
	global_load_dword v162, v[178:179], off
	v_lshl_add_u64 v[178:179], v[178:179], 0, s[98:99]
	global_load_dword v164, v[178:179], off
	v_lshl_add_u64 v[178:179], v[178:179], 0, s[98:99]
	global_load_dword v166, v[178:179], off
	v_lshl_add_u64 v[178:179], v[178:179], 0, s[98:99]
	global_load_dword v168, v[178:179], off
	v_lshl_add_u64 v[178:179], v[178:179], 0, s[98:99]
	global_load_dword v170, v[178:179], off
	v_lshl_add_u64 v[178:179], v[178:179], 0, s[98:99]
	global_load_dword v172, v[178:179], off
	v_lshl_add_u64 v[178:179], v[178:179], 0, s[98:99]
	global_load_dword v174, v[178:179], off
	v_lshl_add_u64 v[178:179], v[178:179], 0, s[98:99]
	global_load_dword v176, v[178:179], off
	s_waitcnt vmcnt(24)
.Lmod_nopf0:
	v_mov_b32_e32 v17, s10
	ds_read_b128 v[18:21], v17
	ds_read_b128 v[22:25], v17 offset:16
	ds_read_b128 v[26:29], v17 offset:4096
	ds_read_b128 v[30:33], v17 offset:4112
	ds_read_b128 v[34:37], v17 offset:8192
	ds_read_b128 v[38:41], v17 offset:8208
	ds_read_b128 v[42:45], v17 offset:12288
	ds_read_b128 v[46:49], v17 offset:12304
	ds_read_b128 v[50:53], v17 offset:16384
	ds_read_b128 v[54:57], v17 offset:16400
	ds_read_b128 v[58:61], v17 offset:20480
	ds_read_b128 v[62:65], v17 offset:20496
	ds_read_b128 v[66:69], v17 offset:24576
	ds_read_b128 v[70:73], v17 offset:24592
	ds_read_b128 v[74:77], v17 offset:28672
	ds_read_b128 v[78:81], v17 offset:28688
	s_waitcnt lgkmcnt(0)
	v_mov_b32_e32 v98, v18
	s_waitcnt lgkmcnt(13)
	v_mov_b32_e32 v99, v26
	v_mov_b32_e32 v26, v19
	v_mov_b32_e32 v18, v20
	v_mov_b32_e32 v19, v28
	v_mov_b32_e32 v28, v21
	s_waitcnt lgkmcnt(11)
	v_mov_b32_e32 v20, v34
	s_waitcnt lgkmcnt(9)
	v_mov_b32_e32 v21, v42
	v_mov_b32_e32 v42, v35
	v_mov_b32_e32 v34, v36
	v_mov_b32_e32 v35, v44
	v_mov_b32_e32 v44, v37
	s_waitcnt lgkmcnt(7)
	v_mov_b32_e32 v36, v50
	s_waitcnt lgkmcnt(5)
	v_mov_b32_e32 v37, v58
	v_mov_b32_e32 v58, v51
	v_mov_b32_e32 v50, v52
	v_mov_b32_e32 v51, v60
	v_mov_b32_e32 v60, v53
	s_waitcnt lgkmcnt(3)
	v_mov_b32_e32 v52, v66
	s_waitcnt lgkmcnt(1)
	v_mov_b32_e32 v53, v74
	v_mov_b32_e32 v74, v67
	v_mov_b32_e32 v66, v68
	v_mov_b32_e32 v67, v76
	v_mov_b32_e32 v76, v69
	v_mov_b32_e32 v68, v22
	v_mov_b32_e32 v69, v30
	v_mov_b32_e32 v30, v23
	v_mov_b32_e32 v22, v24
	v_mov_b32_e32 v23, v32
	v_mov_b32_e32 v32, v25
	v_mov_b32_e32 v24, v38
	v_mov_b32_e32 v25, v46
	v_mov_b32_e32 v46, v39
	v_mov_b32_e32 v38, v40
	v_mov_b32_e32 v39, v48
	v_mov_b32_e32 v48, v41
	v_mov_b32_e32 v40, v54
	v_mov_b32_e32 v41, v62
	v_mov_b32_e32 v62, v55
	v_mov_b32_e32 v54, v56
	v_mov_b32_e32 v55, v64
	v_mov_b32_e32 v64, v57
	v_mov_b32_e32 v56, v70
	s_waitcnt lgkmcnt(0)
	v_mov_b32_e32 v57, v78
	v_mov_b32_e32 v78, v71
	s_add_u32 s4, s4, 0x30000
	v_mov_b32_e32 v70, v72
	v_mov_b32_e32 v71, v80
	s_addc_u32 s5, s5, 0
	s_add_i32 s10, s10, 32
	v_mov_b32_e32 v80, v73
	s_cmp_eq_u32 s4, 0x300000
	v_pk_fma_f32 v[8:9], v[100:101], v[98:99], v[8:9] op_sel_hi:[0,1,1]
	v_pk_fma_f32 v[10:11], v[100:101], v[20:21], v[10:11] op_sel_hi:[0,1,1]
	v_pk_fma_f32 v[12:13], v[100:101], v[36:37], v[12:13] op_sel_hi:[0,1,1]
	v_pk_fma_f32 v[6:7], v[100:101], v[52:53], v[6:7] op_sel_hi:[0,1,1]
	v_pk_fma_f32 v[8:9], v[102:103], v[26:27], v[8:9] op_sel_hi:[0,1,1]
	v_pk_fma_f32 v[10:11], v[102:103], v[42:43], v[10:11] op_sel_hi:[0,1,1]
	v_pk_fma_f32 v[12:13], v[102:103], v[58:59], v[12:13] op_sel_hi:[0,1,1]
	v_pk_fma_f32 v[6:7], v[102:103], v[74:75], v[6:7] op_sel_hi:[0,1,1]
	v_pk_fma_f32 v[8:9], v[104:105], v[18:19], v[8:9] op_sel_hi:[0,1,1]
	v_pk_fma_f32 v[10:11], v[104:105], v[34:35], v[10:11] op_sel_hi:[0,1,1]
	v_pk_fma_f32 v[12:13], v[104:105], v[50:51], v[12:13] op_sel_hi:[0,1,1]
	v_pk_fma_f32 v[6:7], v[104:105], v[66:67], v[6:7] op_sel_hi:[0,1,1]
	v_pk_fma_f32 v[8:9], v[106:107], v[28:29], v[8:9] op_sel_hi:[0,1,1]
	v_pk_fma_f32 v[10:11], v[106:107], v[44:45], v[10:11] op_sel_hi:[0,1,1]
	v_pk_fma_f32 v[12:13], v[106:107], v[60:61], v[12:13] op_sel_hi:[0,1,1]
	v_pk_fma_f32 v[6:7], v[106:107], v[76:77], v[6:7] op_sel_hi:[0,1,1]
	v_pk_fma_f32 v[8:9], v[108:109], v[68:69], v[8:9] op_sel_hi:[0,1,1]
	v_pk_fma_f32 v[10:11], v[108:109], v[24:25], v[10:11] op_sel_hi:[0,1,1]
	v_pk_fma_f32 v[12:13], v[108:109], v[40:41], v[12:13] op_sel_hi:[0,1,1]
	v_pk_fma_f32 v[6:7], v[108:109], v[56:57], v[6:7] op_sel_hi:[0,1,1]
	v_pk_fma_f32 v[8:9], v[110:111], v[30:31], v[8:9] op_sel_hi:[0,1,1]
	v_pk_fma_f32 v[10:11], v[110:111], v[46:47], v[10:11] op_sel_hi:[0,1,1]
	v_pk_fma_f32 v[12:13], v[110:111], v[62:63], v[12:13] op_sel_hi:[0,1,1]
	v_pk_fma_f32 v[6:7], v[110:111], v[78:79], v[6:7] op_sel_hi:[0,1,1]
	v_pk_fma_f32 v[8:9], v[112:113], v[22:23], v[8:9] op_sel_hi:[0,1,1]
	v_pk_fma_f32 v[10:11], v[112:113], v[38:39], v[10:11] op_sel_hi:[0,1,1]
	v_pk_fma_f32 v[12:13], v[112:113], v[54:55], v[12:13] op_sel_hi:[0,1,1]
	v_pk_fma_f32 v[6:7], v[112:113], v[70:71], v[6:7] op_sel_hi:[0,1,1]
	v_pk_fma_f32 v[8:9], v[114:115], v[32:33], v[8:9] op_sel_hi:[0,1,1]
	v_pk_fma_f32 v[10:11], v[114:115], v[48:49], v[10:11] op_sel_hi:[0,1,1]
	v_pk_fma_f32 v[12:13], v[114:115], v[64:65], v[12:13] op_sel_hi:[0,1,1]
	v_pk_fma_f32 v[6:7], v[114:115], v[80:81], v[6:7] op_sel_hi:[0,1,1]
	s_cmp_lt_u32 s4, 0x270000
	s_cbranch_scc0 .Lmod_nopf1
	v_lshl_add_u64 v[178:179], v[4:5], 0, s[4:5]
	s_mov_b64 s[98:99], 0x90000
	v_lshl_add_u64 v[178:179], v[178:179], 0, s[98:99]
	s_mov_b64 s[98:99], 0x6000
	global_load_dword v100, v[178:179], off
	v_lshl_add_u64 v[178:179], v[178:179], 0, s[98:99]
	global_load_dword v102, v[178:179], off
	v_lshl_add_u64 v[178:179], v[178:179], 0, s[98:99]
	global_load_dword v104, v[178:179], off
	v_lshl_add_u64 v[178:179], v[178:179], 0, s[98:99]
	global_load_dword v106, v[178:179], off
	v_lshl_add_u64 v[178:179], v[178:179], 0, s[98:99]
	global_load_dword v108, v[178:179], off
	v_lshl_add_u64 v[178:179], v[178:179], 0, s[98:99]
	global_load_dword v110, v[178:179], off
	v_lshl_add_u64 v[178:179], v[178:179], 0, s[98:99]
	global_load_dword v112, v[178:179], off
	v_lshl_add_u64 v[178:179], v[178:179], 0, s[98:99]
	global_load_dword v114, v[178:179], off
	s_waitcnt vmcnt(24)
	s_branch .Lmod_go1
.Lmod_nopf1:
	s_waitcnt vmcnt(16)
.Lmod_go1:
	v_mov_b32_e32 v17, s10
	ds_read_b128 v[18:21], v17
	ds_read_b128 v[22:25], v17 offset:16
	ds_read_b128 v[26:29], v17 offset:4096
	ds_read_b128 v[30:33], v17 offset:4112
	ds_read_b128 v[34:37], v17 offset:8192
	ds_read_b128 v[38:41], v17 offset:8208
	ds_read_b128 v[42:45], v17 offset:12288
	ds_read_b128 v[46:49], v17 offset:12304
	ds_read_b128 v[50:53], v17 offset:16384
	ds_read_b128 v[54:57], v17 offset:16400
	ds_read_b128 v[58:61], v17 offset:20480
	ds_read_b128 v[62:65], v17 offset:20496
	ds_read_b128 v[66:69], v17 offset:24576
	ds_read_b128 v[70:73], v17 offset:24592
	ds_read_b128 v[74:77], v17 offset:28672
	ds_read_b128 v[78:81], v17 offset:28688
	s_waitcnt lgkmcnt(0)
	v_mov_b32_e32 v98, v18
	s_waitcnt lgkmcnt(13)
	v_mov_b32_e32 v99, v26
	v_mov_b32_e32 v26, v19
	v_mov_b32_e32 v18, v20
	v_mov_b32_e32 v19, v28
	v_mov_b32_e32 v28, v21
	s_waitcnt lgkmcnt(11)
	v_mov_b32_e32 v20, v34
	s_waitcnt lgkmcnt(9)
	v_mov_b32_e32 v21, v42
	v_mov_b32_e32 v42, v35
	v_mov_b32_e32 v34, v36
	v_mov_b32_e32 v35, v44
	v_mov_b32_e32 v44, v37
	s_waitcnt lgkmcnt(7)
	v_mov_b32_e32 v36, v50
	s_waitcnt lgkmcnt(5)
	v_mov_b32_e32 v37, v58
	v_mov_b32_e32 v58, v51
	v_mov_b32_e32 v50, v52
	v_mov_b32_e32 v51, v60
	v_mov_b32_e32 v60, v53
	s_waitcnt lgkmcnt(3)
	v_mov_b32_e32 v52, v66
	s_waitcnt lgkmcnt(1)
	v_mov_b32_e32 v53, v74
	v_mov_b32_e32 v74, v67
	v_mov_b32_e32 v66, v68
	v_mov_b32_e32 v67, v76
	v_mov_b32_e32 v76, v69
	v_mov_b32_e32 v68, v22
	v_mov_b32_e32 v69, v30
	v_mov_b32_e32 v30, v23
	v_mov_b32_e32 v22, v24
	v_mov_b32_e32 v23, v32
	v_mov_b32_e32 v32, v25
	v_mov_b32_e32 v24, v38
	v_mov_b32_e32 v25, v46
	v_mov_b32_e32 v46, v39
	v_mov_b32_e32 v38, v40
	v_mov_b32_e32 v39, v48
	v_mov_b32_e32 v48, v41
	v_mov_b32_e32 v40, v54
	v_mov_b32_e32 v41, v62
	v_mov_b32_e32 v62, v55
	v_mov_b32_e32 v54, v56
	v_mov_b32_e32 v55, v64
	v_mov_b32_e32 v64, v57
	v_mov_b32_e32 v56, v70
	s_waitcnt lgkmcnt(0)
	v_mov_b32_e32 v57, v78
	v_mov_b32_e32 v78, v71
	s_add_u32 s4, s4, 0x30000
	v_mov_b32_e32 v70, v72
	v_mov_b32_e32 v71, v80
	s_addc_u32 s5, s5, 0
	s_add_i32 s10, s10, 32
	v_mov_b32_e32 v80, v73
	s_cmp_eq_u32 s4, 0x300000
	v_pk_fma_f32 v[8:9], v[116:117], v[98:99], v[8:9] op_sel_hi:[0,1,1]
	v_pk_fma_f32 v[10:11], v[116:117], v[20:21], v[10:11] op_sel_hi:[0,1,1]
	v_pk_fma_f32 v[12:13], v[116:117], v[36:37], v[12:13] op_sel_hi:[0,1,1]
	v_pk_fma_f32 v[6:7], v[116:117], v[52:53], v[6:7] op_sel_hi:[0,1,1]
	v_pk_fma_f32 v[8:9], v[118:119], v[26:27], v[8:9] op_sel_hi:[0,1,1]
	v_pk_fma_f32 v[10:11], v[118:119], v[42:43], v[10:11] op_sel_hi:[0,1,1]
	v_pk_fma_f32 v[12:13], v[118:119], v[58:59], v[12:13] op_sel_hi:[0,1,1]
	v_pk_fma_f32 v[6:7], v[118:119], v[74:75], v[6:7] op_sel_hi:[0,1,1]
	v_pk_fma_f32 v[8:9], v[120:121], v[18:19], v[8:9] op_sel_hi:[0,1,1]
	v_pk_fma_f32 v[10:11], v[120:121], v[34:35], v[10:11] op_sel_hi:[0,1,1]
	v_pk_fma_f32 v[12:13], v[120:121], v[50:51], v[12:13] op_sel_hi:[0,1,1]
	v_pk_fma_f32 v[6:7], v[120:121], v[66:67], v[6:7] op_sel_hi:[0,1,1]
	v_pk_fma_f32 v[8:9], v[122:123], v[28:29], v[8:9] op_sel_hi:[0,1,1]
	v_pk_fma_f32 v[10:11], v[122:123], v[44:45], v[10:11] op_sel_hi:[0,1,1]
	v_pk_fma_f32 v[12:13], v[122:123], v[60:61], v[12:13] op_sel_hi:[0,1,1]
	v_pk_fma_f32 v[6:7], v[122:123], v[76:77], v[6:7] op_sel_hi:[0,1,1]
	v_pk_fma_f32 v[8:9], v[124:125], v[68:69], v[8:9] op_sel_hi:[0,1,1]
	v_pk_fma_f32 v[10:11], v[124:125], v[24:25], v[10:11] op_sel_hi:[0,1,1]
	v_pk_fma_f32 v[12:13], v[124:125], v[40:41], v[12:13] op_sel_hi:[0,1,1]
	v_pk_fma_f32 v[6:7], v[124:125], v[56:57], v[6:7] op_sel_hi:[0,1,1]
	v_pk_fma_f32 v[8:9], v[126:127], v[30:31], v[8:9] op_sel_hi:[0,1,1]
	v_pk_fma_f32 v[10:11], v[126:127], v[46:47], v[10:11] op_sel_hi:[0,1,1]
	v_pk_fma_f32 v[12:13], v[126:127], v[62:63], v[12:13] op_sel_hi:[0,1,1]
	v_pk_fma_f32 v[6:7], v[126:127], v[78:79], v[6:7] op_sel_hi:[0,1,1]
	v_pk_fma_f32 v[8:9], v[128:129], v[22:23], v[8:9] op_sel_hi:[0,1,1]
	v_pk_fma_f32 v[10:11], v[128:129], v[38:39], v[10:11] op_sel_hi:[0,1,1]
	v_pk_fma_f32 v[12:13], v[128:129], v[54:55], v[12:13] op_sel_hi:[0,1,1]
	v_pk_fma_f32 v[6:7], v[128:129], v[70:71], v[6:7] op_sel_hi:[0,1,1]
	v_pk_fma_f32 v[8:9], v[130:131], v[32:33], v[8:9] op_sel_hi:[0,1,1]
	v_pk_fma_f32 v[10:11], v[130:131], v[48:49], v[10:11] op_sel_hi:[0,1,1]
	v_pk_fma_f32 v[12:13], v[130:131], v[64:65], v[12:13] op_sel_hi:[0,1,1]
	v_pk_fma_f32 v[6:7], v[130:131], v[80:81], v[6:7] op_sel_hi:[0,1,1]
	s_cmp_lt_u32 s4, 0x270000
	s_cbranch_scc0 .Lmod_nopf2
	v_lshl_add_u64 v[178:179], v[4:5], 0, s[4:5]
	s_mov_b64 s[98:99], 0x90000
	v_lshl_add_u64 v[178:179], v[178:179], 0, s[98:99]
	s_mov_b64 s[98:99], 0x6000
	global_load_dword v116, v[178:179], off
	v_lshl_add_u64 v[178:179], v[178:179], 0, s[98:99]
	global_load_dword v118, v[178:179], off
	v_lshl_add_u64 v[178:179], v[178:179], 0, s[98:99]
	global_load_dword v120, v[178:179], off
	v_lshl_add_u64 v[178:179], v[178:179], 0, s[98:99]
	global_load_dword v122, v[178:179], off
	v_lshl_add_u64 v[178:179], v[178:179], 0, s[98:99]
	global_load_dword v124, v[178:179], off
	v_lshl_add_u64 v[178:179], v[178:179], 0, s[98:99]
	global_load_dword v126, v[178:179], off
	v_lshl_add_u64 v[178:179], v[178:179], 0, s[98:99]
	global_load_dword v128, v[178:179], off
	v_lshl_add_u64 v[178:179], v[178:179], 0, s[98:99]
	global_load_dword v130, v[178:179], off
	s_waitcnt vmcnt(24)
	s_branch .Lmod_go2

.Lmod_go2:
	v_mov_b32_e32 v17, s10
	ds_read_b128 v[18:21], v17
	ds_read_b128 v[22:25], v17 offset:16
	ds_read_b128 v[26:29], v17 offset:4096
	ds_read_b128 v[30:33], v17 offset:4112
	ds_read_b128 v[34:37], v17 offset:8192
	ds_read_b128 v[38:41], v17 offset:8208
	ds_read_b128 v[42:45], v17 offset:12288
	ds_read_b128 v[46:49], v17 offset:12304
	ds_read_b128 v[50:53], v17 offset:16384
	ds_read_b128 v[54:57], v17 offset:16400
	ds_read_b128 v[58:61], v17 offset:20480
	ds_read_b128 v[62:65], v17 offset:20496
	ds_read_b128 v[66:69], v17 offset:24576
	ds_read_b128 v[70:73], v17 offset:24592
	ds_read_b128 v[74:77], v17 offset:28672
	ds_read_b128 v[78:81], v17 offset:28688
	s_waitcnt lgkmcnt(0)
	v_mov_b32_e32 v98, v18
	s_waitcnt lgkmcnt(13)
	v_mov_b32_e32 v99, v26
	v_mov_b32_e32 v26, v19
	v_mov_b32_e32 v18, v20
	v_mov_b32_e32 v19, v28
	v_mov_b32_e32 v28, v21
	s_waitcnt lgkmcnt(11)
	v_mov_b32_e32 v20, v34
	s_waitcnt lgkmcnt(9)
	v_mov_b32_e32 v21, v42
	v_mov_b32_e32 v42, v35
	v_mov_b32_e32 v34, v36
	v_mov_b32_e32 v35, v44
	v_mov_b32_e32 v44, v37
	s_waitcnt lgkmcnt(7)
	v_mov_b32_e32 v36, v50
	s_waitcnt lgkmcnt(5)
	v_mov_b32_e32 v37, v58
	v_mov_b32_e32 v58, v51
	v_mov_b32_e32 v50, v52
	v_mov_b32_e32 v51, v60
	v_mov_b32_e32 v60, v53
	s_waitcnt lgkmcnt(3)
	v_mov_b32_e32 v52, v66
	s_waitcnt lgkmcnt(1)
	v_mov_b32_e32 v53, v74
	v_mov_b32_e32 v74, v67
	v_mov_b32_e32 v66, v68
	v_mov_b32_e32 v67, v76
	v_mov_b32_e32 v76, v69
	v_mov_b32_e32 v68, v22
	v_mov_b32_e32 v69, v30
	v_mov_b32_e32 v30, v23
	v_mov_b32_e32 v22, v24
	v_mov_b32_e32 v23, v32
	v_mov_b32_e32 v32, v25
	v_mov_b32_e32 v24, v38
	v_mov_b32_e32 v25, v46
	v_mov_b32_e32 v46, v39
	v_mov_b32_e32 v38, v40
	v_mov_b32_e32 v39, v48
	v_mov_b32_e32 v48, v41
	v_mov_b32_e32 v40, v54
	v_mov_b32_e32 v41, v62
	v_mov_b32_e32 v62, v55
	v_mov_b32_e32 v54, v56
	v_mov_b32_e32 v55, v64
	v_mov_b32_e32 v64, v57
	v_mov_b32_e32 v56, v70
	s_waitcnt lgkmcnt(0)
	v_mov_b32_e32 v57, v78
	v_mov_b32_e32 v78, v71
	s_add_u32 s4, s4, 0x30000
	v_mov_b32_e32 v70, v72
	v_mov_b32_e32 v71, v80
	s_addc_u32 s5, s5, 0
	s_add_i32 s10, s10, 32
	v_mov_b32_e32 v80, v73
	s_cmp_eq_u32 s4, 0x300000
	v_pk_fma_f32 v[8:9], v[132:133], v[98:99], v[8:9] op_sel_hi:[0,1,1]
	v_pk_fma_f32 v[10:11], v[132:133], v[20:21], v[10:11] op_sel_hi:[0,1,1]
	v_pk_fma_f32 v[12:13], v[132:133], v[36:37], v[12:13] op_sel_hi:[0,1,1]
	v_pk_fma_f32 v[6:7], v[132:133], v[52:53], v[6:7] op_sel_hi:[0,1,1]
	v_pk_fma_f32 v[8:9], v[134:135], v[26:27], v[8:9] op_sel_hi:[0,1,1]
	v_pk_fma_f32 v[10:11], v[134:135], v[42:43], v[10:11] op_sel_hi:[0,1,1]
	v_pk_fma_f32 v[12:13], v[134:135], v[58:59], v[12:13] op_sel_hi:[0,1,1]
	v_pk_fma_f32 v[6:7], v[134:135], v[74:75], v[6:7] op_sel_hi:[0,1,1]
	v_pk_fma_f32 v[8:9], v[136:137], v[18:19], v[8:9] op_sel_hi:[0,1,1]
	v_pk_fma_f32 v[10:11], v[136:137], v[34:35], v[10:11] op_sel_hi:[0,1,1]
	v_pk_fma_f32 v[12:13], v[136:137], v[50:51], v[12:13] op_sel_hi:[0,1,1]
	v_pk_fma_f32 v[6:7], v[136:137], v[66:67], v[6:7] op_sel_hi:[0,1,1]
	v_pk_fma_f32 v[8:9], v[138:139], v[28:29], v[8:9] op_sel_hi:[0,1,1]
	v_pk_fma_f32 v[10:11], v[138:139], v[44:45], v[10:11] op_sel_hi:[0,1,1]
	v_pk_fma_f32 v[12:13], v[138:139], v[60:61], v[12:13] op_sel_hi:[0,1,1]
	v_pk_fma_f32 v[6:7], v[138:139], v[76:77], v[6:7] op_sel_hi:[0,1,1]
	v_pk_fma_f32 v[8:9], v[140:141], v[68:69], v[8:9] op_sel_hi:[0,1,1]
	v_pk_fma_f32 v[10:11], v[140:141], v[24:25], v[10:11] op_sel_hi:[0,1,1]
	v_pk_fma_f32 v[12:13], v[140:141], v[40:41], v[12:13] op_sel_hi:[0,1,1]
	v_pk_fma_f32 v[6:7], v[140:141], v[56:57], v[6:7] op_sel_hi:[0,1,1]
	v_pk_fma_f32 v[8:9], v[142:143], v[30:31], v[8:9] op_sel_hi:[0,1,1]
	v_pk_fma_f32 v[10:11], v[142:143], v[46:47], v[10:11] op_sel_hi:[0,1,1]
	v_pk_fma_f32 v[12:13], v[142:143], v[62:63], v[12:13] op_sel_hi:[0,1,1]
	v_pk_fma_f32 v[6:7], v[142:143], v[78:79], v[6:7] op_sel_hi:[0,1,1]
	v_pk_fma_f32 v[8:9], v[144:145], v[22:23], v[8:9] op_sel_hi:[0,1,1]
	v_pk_fma_f32 v[10:11], v[144:145], v[38:39], v[10:11] op_sel_hi:[0,1,1]
	v_pk_fma_f32 v[12:13], v[144:145], v[54:55], v[12:13] op_sel_hi:[0,1,1]
	v_pk_fma_f32 v[6:7], v[144:145], v[70:71], v[6:7] op_sel_hi:[0,1,1]
	v_pk_fma_f32 v[8:9], v[146:147], v[32:33], v[8:9] op_sel_hi:[0,1,1]
	v_pk_fma_f32 v[10:11], v[146:147], v[48:49], v[10:11] op_sel_hi:[0,1,1]
	v_pk_fma_f32 v[12:13], v[146:147], v[64:65], v[12:13] op_sel_hi:[0,1,1]
	v_pk_fma_f32 v[6:7], v[146:147], v[80:81], v[6:7] op_sel_hi:[0,1,1]
	s_cmp_lt_u32 s4, 0x270000
	s_cbranch_scc0 .Lmod_nopf3
	v_lshl_add_u64 v[178:179], v[4:5], 0, s[4:5]
	s_mov_b64 s[98:99], 0x90000
	v_lshl_add_u64 v[178:179], v[178:179], 0, s[98:99]
	s_mov_b64 s[98:99], 0x6000
	global_load_dword v132, v[178:179], off
	v_lshl_add_u64 v[178:179], v[178:179], 0, s[98:99]
	global_load_dword v134, v[178:179], off
	v_lshl_add_u64 v[178:179], v[178:179], 0, s[98:99]
	global_load_dword v136, v[178:179], off
	v_lshl_add_u64 v[178:179], v[178:179], 0, s[98:99]
	global_load_dword v138, v[178:179], off
	v_lshl_add_u64 v[178:179], v[178:179], 0, s[98:99]
	global_load_dword v140, v[178:179], off
	v_lshl_add_u64 v[178:179], v[178:179], 0, s[98:99]
	global_load_dword v142, v[178:179], off
	v_lshl_add_u64 v[178:179], v[178:179], 0, s[98:99]
	global_load_dword v144, v[178:179], off
	v_lshl_add_u64 v[178:179], v[178:179], 0, s[98:99]
	global_load_dword v146, v[178:179], off
	s_waitcnt vmcnt(24)
	s_branch .Lmod_go3

.Lmod_go3:
	v_mov_b32_e32 v17, s10
	ds_read_b128 v[18:21], v17
	ds_read_b128 v[22:25], v17 offset:16
	ds_read_b128 v[26:29], v17 offset:4096
	ds_read_b128 v[30:33], v17 offset:4112
	ds_read_b128 v[34:37], v17 offset:8192
	ds_read_b128 v[38:41], v17 offset:8208
	ds_read_b128 v[42:45], v17 offset:12288
	ds_read_b128 v[46:49], v17 offset:12304
	ds_read_b128 v[50:53], v17 offset:16384
	ds_read_b128 v[54:57], v17 offset:16400
	ds_read_b128 v[58:61], v17 offset:20480
	ds_read_b128 v[62:65], v17 offset:20496
	ds_read_b128 v[66:69], v17 offset:24576
	ds_read_b128 v[70:73], v17 offset:24592
	ds_read_b128 v[74:77], v17 offset:28672
	ds_read_b128 v[78:81], v17 offset:28688
	s_waitcnt lgkmcnt(0)
	v_mov_b32_e32 v98, v18
	s_waitcnt lgkmcnt(13)
	v_mov_b32_e32 v99, v26
	v_mov_b32_e32 v26, v19
	v_mov_b32_e32 v18, v20
	v_mov_b32_e32 v19, v28
	v_mov_b32_e32 v28, v21
	s_waitcnt lgkmcnt(11)
	v_mov_b32_e32 v20, v34
	s_waitcnt lgkmcnt(9)
	v_mov_b32_e32 v21, v42
	v_mov_b32_e32 v42, v35
	v_mov_b32_e32 v34, v36
	v_mov_b32_e32 v35, v44
	v_mov_b32_e32 v44, v37
	s_waitcnt lgkmcnt(7)
	v_mov_b32_e32 v36, v50
	s_waitcnt lgkmcnt(5)
	v_mov_b32_e32 v37, v58
	v_mov_b32_e32 v58, v51
	v_mov_b32_e32 v50, v52
	v_mov_b32_e32 v51, v60
	v_mov_b32_e32 v60, v53
	s_waitcnt lgkmcnt(3)
	v_mov_b32_e32 v52, v66
	s_waitcnt lgkmcnt(1)
	v_mov_b32_e32 v53, v74
	v_mov_b32_e32 v74, v67
	v_mov_b32_e32 v66, v68
	v_mov_b32_e32 v67, v76
	v_mov_b32_e32 v76, v69
	v_mov_b32_e32 v68, v22
	v_mov_b32_e32 v69, v30
	v_mov_b32_e32 v30, v23
	v_mov_b32_e32 v22, v24
	v_mov_b32_e32 v23, v32
	v_mov_b32_e32 v32, v25
	v_mov_b32_e32 v24, v38
	v_mov_b32_e32 v25, v46
	v_mov_b32_e32 v46, v39
	v_mov_b32_e32 v38, v40
	v_mov_b32_e32 v39, v48
	v_mov_b32_e32 v48, v41
	v_mov_b32_e32 v40, v54
	v_mov_b32_e32 v41, v62
	v_mov_b32_e32 v62, v55
	v_mov_b32_e32 v54, v56
	v_mov_b32_e32 v55, v64
	v_mov_b32_e32 v64, v57
	v_mov_b32_e32 v56, v70
	s_waitcnt lgkmcnt(0)
	v_mov_b32_e32 v57, v78
	v_mov_b32_e32 v78, v71
	s_add_u32 s4, s4, 0x30000
	v_mov_b32_e32 v70, v72
	v_mov_b32_e32 v71, v80
	s_addc_u32 s5, s5, 0
	s_add_i32 s10, s10, 32
	v_mov_b32_e32 v80, v73
	s_cmp_eq_u32 s4, 0x300000
	v_pk_fma_f32 v[8:9], v[162:163], v[98:99], v[8:9] op_sel_hi:[0,1,1]
	v_pk_fma_f32 v[10:11], v[162:163], v[20:21], v[10:11] op_sel_hi:[0,1,1]
	v_pk_fma_f32 v[12:13], v[162:163], v[36:37], v[12:13] op_sel_hi:[0,1,1]
	v_pk_fma_f32 v[6:7], v[162:163], v[52:53], v[6:7] op_sel_hi:[0,1,1]
	v_pk_fma_f32 v[8:9], v[164:165], v[26:27], v[8:9] op_sel_hi:[0,1,1]
	v_pk_fma_f32 v[10:11], v[164:165], v[42:43], v[10:11] op_sel_hi:[0,1,1]
	v_pk_fma_f32 v[12:13], v[164:165], v[58:59], v[12:13] op_sel_hi:[0,1,1]
	v_pk_fma_f32 v[6:7], v[164:165], v[74:75], v[6:7] op_sel_hi:[0,1,1]
	v_pk_fma_f32 v[8:9], v[166:167], v[18:19], v[8:9] op_sel_hi:[0,1,1]
	v_pk_fma_f32 v[10:11], v[166:167], v[34:35], v[10:11] op_sel_hi:[0,1,1]
	v_pk_fma_f32 v[12:13], v[166:167], v[50:51], v[12:13] op_sel_hi:[0,1,1]
	v_pk_fma_f32 v[6:7], v[166:167], v[66:67], v[6:7] op_sel_hi:[0,1,1]
	v_pk_fma_f32 v[8:9], v[168:169], v[28:29], v[8:9] op_sel_hi:[0,1,1]
	v_pk_fma_f32 v[10:11], v[168:169], v[44:45], v[10:11] op_sel_hi:[0,1,1]
	v_pk_fma_f32 v[12:13], v[168:169], v[60:61], v[12:13] op_sel_hi:[0,1,1]
	v_pk_fma_f32 v[6:7], v[168:169], v[76:77], v[6:7] op_sel_hi:[0,1,1]
	v_pk_fma_f32 v[8:9], v[170:171], v[68:69], v[8:9] op_sel_hi:[0,1,1]
	v_pk_fma_f32 v[10:11], v[170:171], v[24:25], v[10:11] op_sel_hi:[0,1,1]
	v_pk_fma_f32 v[12:13], v[170:171], v[40:41], v[12:13] op_sel_hi:[0,1,1]
	v_pk_fma_f32 v[6:7], v[170:171], v[56:57], v[6:7] op_sel_hi:[0,1,1]
	v_pk_fma_f32 v[8:9], v[172:173], v[30:31], v[8:9] op_sel_hi:[0,1,1]
	v_pk_fma_f32 v[10:11], v[172:173], v[46:47], v[10:11] op_sel_hi:[0,1,1]
	v_pk_fma_f32 v[12:13], v[172:173], v[62:63], v[12:13] op_sel_hi:[0,1,1]
	v_pk_fma_f32 v[6:7], v[172:173], v[78:79], v[6:7] op_sel_hi:[0,1,1]
	v_pk_fma_f32 v[8:9], v[174:175], v[22:23], v[8:9] op_sel_hi:[0,1,1]
	v_pk_fma_f32 v[10:11], v[174:175], v[38:39], v[10:11] op_sel_hi:[0,1,1]
	v_pk_fma_f32 v[12:13], v[174:175], v[54:55], v[12:13] op_sel_hi:[0,1,1]
	v_pk_fma_f32 v[6:7], v[174:175], v[70:71], v[6:7] op_sel_hi:[0,1,1]
	v_pk_fma_f32 v[8:9], v[176:177], v[32:33], v[8:9] op_sel_hi:[0,1,1]
	v_pk_fma_f32 v[10:11], v[176:177], v[48:49], v[10:11] op_sel_hi:[0,1,1]
	v_pk_fma_f32 v[12:13], v[176:177], v[64:65], v[12:13] op_sel_hi:[0,1,1]
	v_pk_fma_f32 v[6:7], v[176:177], v[80:81], v[6:7] op_sel_hi:[0,1,1]
	s_cbranch_scc0 .LBB0_447
	s_mul_i32 s4, s9, 0x1800
	v_add_u32_e32 v4, s6, v14
	s_add_i32 s4, s4, s0
	ds_write2st64_b32 v4, v8, v9 offset0:128 offset1:129
	ds_write2st64_b32 v4, v10, v11 offset0:130 offset1:131
	ds_write2st64_b32 v4, v12, v13 offset0:132 offset1:133
	ds_write2st64_b32 v4, v6, v7 offset0:134 offset1:135
	v_or_b32_e32 v4, s4, v160
	v_readlane_b32 s64, v253, 62
	v_ashrrev_i32_e32 v5, 31, v4
	v_readlane_b32 s70, v254, 4
	v_readlane_b32 s71, v254, 5
	s_waitcnt lgkmcnt(0)
	s_barrier
	v_lshl_add_u64 v[4:5], v[4:5], 2, s[70:71]
	global_load_dword v17, v[4:5], off
	ds_read2st64_b32 v[6:7], v16 offset0:128 offset1:136
	ds_read2st64_b32 v[8:9], v16 offset0:144 offset1:152
	ds_read2st64_b32 v[10:11], v16 offset0:160 offset1:168
	ds_read2st64_b32 v[12:13], v16 offset0:176 offset1:184
	v_lshl_add_u32 v18, s9, 3, v15
	v_mov_b64_e32 v[4:5], s[82:83]
	v_mad_i64_i32 v[4:5], s[4:5], v18, s50, v[4:5]
	s_add_i32 s8, s8, s36
	v_lshl_add_u64 v[4:5], s[0:1], 2, v[4:5]
	s_cmpk_gt_i32 s8, 0x17f
	v_lshl_add_u64 v[4:5], v[4:5], 0, v[0:1]
	v_readlane_b32 s65, v253, 63
	v_readlane_b32 s66, v254, 0
	v_readlane_b32 s67, v254, 1
	v_readlane_b32 s68, v254, 2
	v_readlane_b32 s69, v254, 3
	v_readlane_b32 s72, v254, 6
	v_readlane_b32 s73, v254, 7
	v_readlane_b32 s74, v254, 8
	v_readlane_b32 s75, v254, 9
	v_readlane_b32 s76, v254, 10
	v_readlane_b32 s77, v254, 11
	v_readlane_b32 s78, v254, 12
	v_readlane_b32 s79, v254, 13
	s_waitcnt vmcnt(0) lgkmcnt(3)
	v_add_f32_e32 v6, v17, v6
	v_add_f32_e32 v6, v6, v7
	s_waitcnt lgkmcnt(2)
	v_add_f32_e32 v6, v6, v8
	v_add_f32_e32 v6, v6, v9
	s_waitcnt lgkmcnt(1)
	v_add_f32_e32 v6, v6, v10
	v_add_f32_e32 v6, v6, v11
	s_waitcnt lgkmcnt(0)
	v_add_f32_e32 v6, v6, v12
	v_add_f32_e32 v6, v6, v13
	flat_store_dword v[4:5], v6
	s_waitcnt lgkmcnt(0)
	s_barrier
	s_cbranch_scc0 .LBB0_446
	s_movk_i32 s74, 0x8400
	s_movk_i32 s75, 0x8800
	s_movk_i32 s64, 0x8c00
	s_movk_i32 s66, 0x9000
	s_movk_i32 s67, 0x9400
	s_movk_i32 s70, 0x9800
	s_movk_i32 s71, 0x9c00
	s_movk_i32 s68, 0xa000
	s_movk_i32 s69, 0xa400
	s_movk_i32 s72, 0xa800
	s_movk_i32 s73, 0xac00
	s_movk_i32 s76, 0xb000
	s_movk_i32 s77, 0xb400
	s_movk_i32 s65, 0xb800
	s_movk_i32 s20, 0xbc00
	s_movk_i32 s21, 0xc000
	s_movk_i32 s17, 0xc400
	s_movk_i32 s18, 0xc800
	s_movk_i32 s19, 0xcc00
	s_movk_i32 s12, 0xd400
	s_movk_i32 s13, 0xd800
	s_movk_i32 s14, 0xdc00
	s_movk_i32 s15, 0xe000
	s_movk_i32 s16, 0xe800
